# P5 item loop: static s_setprio 1 for the second-dispatched wave half (waves 4-7), reset at the loop exit
# speedup vs baseline: 1.0105x; 1.0105x over previous
.LBB0_426:
	s_add_u32 s22, s16, 0x2000000
	s_addc_u32 s23, s17, 0
	s_add_u32 s44, s16, 0xb000000
	s_addc_u32 s45, s17, 0
	s_cmpk_lg_i32 s52, 0x100
	s_cselect_b64 s[24:25], -1, 0
	s_lshl_b32 s4, s54, 5
	s_and_b32 s47, s4, 32
	s_lshl_b32 s4, s31, 2
	s_add_i32 s48, s4, 0
	s_lshl_b32 s4, s54, 4
	s_add_i32 s51, s54, 8
	s_load_dwordx2 s[14:15], s[18:19], 0x28
	s_load_dwordx2 s[20:21], s[18:19], 0x68
	s_and_b32 s49, s4, 0x3fffffe0
	s_lshl_b32 s4, s51, 4
	s_and_b32 s57, s4, 0x7fffffe0
	s_lshl_b32 s4, s33, 4
	s_add_i32 s60, s4, 16
	s_lshl_b32 s4, s33, 6
	s_add_i32 s61, s4, 64
	s_lshl_b32 s4, s33, 5
	v_cndmask_b32_e64 v2, 0, 1, s[24:25]
	s_ashr_i32 s46, s31, 31
	s_mov_b32 s27, 0
	s_add_i32 s48, s48, 0x20800
	s_lshl_b32 s50, s49, 1
	s_lshl_b32 s59, s57, 1
	s_add_i32 s62, s4, 32
	v_mov_b32_e32 v163, 0
	s_movk_i32 s63, 0x1000
	s_movk_i32 s64, 0x2000
	s_movk_i32 s65, 0x3000
	s_movk_i32 s66, 0x1800
	v_mov_b64_e32 v[164:165], s[12:13]
	s_movk_i32 s67, 0xf0
	s_mov_b64 s[28:29], 0x400
	v_cmp_ne_u32_e64 s[4:5], 1, v2
	s_movk_i32 s68, 0x110
	s_mov_b32 s69, 0x20000
	s_movk_i32 s70, 0x210
	s_mov_b32 s30, 0x3b000000
	s_mov_b32 s34, 0x358637bd
	s_mov_b32 s71, 0x800000
	s_mov_b32 s98, 1
	s_cmp_lt_u32 s54, 4
	s_cbranch_scc1 .Lp5prio_skip
	s_setprio 1
.Lp5prio_skip:
	s_branch .LBB0_428
.LBB0_427:
	s_or_b64 exec, exec, s[6:7]
	v_lshl_add_u32 v70, v169, 2, 0
	v_add_u32_e32 v130, 0x20800, v70
	s_waitcnt lgkmcnt(0)
	s_barrier
	ds_read2_b32 v[70:71], v130 offset1:16
	ds_read2_b32 v[72:73], v130 offset0:64 offset1:80
	ds_read2_b32 v[74:75], v130 offset0:128 offset1:144
	ds_read2_b32 v[76:77], v130 offset0:192 offset1:208
	v_add_u32_e32 v139, 0x400, v130
	s_waitcnt lgkmcnt(3)
	v_mov_b32_e32 v124, v71
	v_mov_b32_e32 v125, v70
	v_pk_add_f32 v[70:71], v[124:125], 0 op_sel_hi:[1,0]
	s_waitcnt lgkmcnt(2)
	v_mov_b32_e32 v124, v73
	v_mov_b32_e32 v125, v72
	ds_read2_b32 v[78:79], v139 offset1:16
	ds_read2_b32 v[80:81], v139 offset0:64 offset1:80
	ds_read2_b32 v[106:107], v139 offset0:128 offset1:144
	ds_read2_b32 v[108:109], v139 offset0:192 offset1:208
	v_pk_add_f32 v[70:71], v[70:71], v[124:125]
	s_waitcnt lgkmcnt(5)
	v_mov_b32_e32 v72, v75
	v_mov_b32_e32 v73, v74
	v_pk_add_f32 v[70:71], v[70:71], v[72:73]
	s_waitcnt lgkmcnt(4)
	v_mov_b32_e32 v72, v77
	v_mov_b32_e32 v73, v76
	v_pk_add_f32 v[70:71], v[70:71], v[72:73]
	s_waitcnt lgkmcnt(3)
	v_mov_b32_e32 v72, v79
	v_mov_b32_e32 v73, v78
	v_pk_add_f32 v[70:71], v[70:71], v[72:73]
	s_waitcnt lgkmcnt(2)
	v_mov_b32_e32 v72, v81
	v_mov_b32_e32 v73, v80
	v_pk_add_f32 v[70:71], v[70:71], v[72:73]
	s_waitcnt lgkmcnt(1)
	v_mov_b32_e32 v72, v107
	v_mov_b32_e32 v73, v106
	v_pk_add_f32 v[70:71], v[70:71], v[72:73]
	s_waitcnt lgkmcnt(0)
	v_mov_b32_e32 v72, v109
	v_mov_b32_e32 v73, v108
	v_pk_add_f32 v[70:71], v[70:71], v[72:73]
	v_mov_b64_e32 v[72:73], s[34:35]
	v_pk_fma_f32 v[70:71], v[70:71], s[30:31], v[72:73] op_sel_hi:[1,0,0]
	v_permlane16_swap_b32_e32 v102, v98
	v_mul_f32_e32 v74, 0x4b800000, v71
	v_cmp_gt_f32_e32 vcc, s71, v71
	v_mul_f32_e32 v76, 0x4b800000, v70
	v_cmp_gt_f32_e64 s[6:7], s71, v70
	v_cndmask_b32_e32 v71, v71, v74, vcc
	v_lshl_add_u64 v[74:75], v[128:129], 2, s[14:15]
	global_load_dwordx4 v[78:81], v[74:75], off offset:16
	global_load_dwordx4 v[106:109], v[74:75], off
	v_rsq_f32_e32 v71, v71
	v_cndmask_b32_e64 v70, v70, v76, s[6:7]
	v_rsq_f32_e32 v148, v70
	v_permlane16_swap_b32_e32 v103, v99
	v_mul_f32_e32 v70, 0x45800000, v71
	v_cndmask_b32_e32 v138, v71, v70, vcc
	ds_read2_b32 v[70:71], v130 offset0:32 offset1:48
	ds_read2_b32 v[76:77], v130 offset0:96 offset1:112
	ds_read2_b32 v[124:125], v130 offset0:160 offset1:176
	ds_read2_b32 v[130:131], v130 offset0:224 offset1:240
	ds_read2_b32 v[134:135], v139 offset0:32 offset1:48
	ds_read2_b32 v[140:141], v139 offset0:96 offset1:112
	ds_read2_b32 v[142:143], v139 offset0:160 offset1:176
	ds_read2_b32 v[144:145], v139 offset0:224 offset1:240
	s_waitcnt lgkmcnt(7)
	v_mov_b32_e32 v146, v71
	v_mov_b32_e32 v147, v70
	v_pk_add_f32 v[70:71], v[146:147], 0 op_sel_hi:[1,0]
	s_waitcnt lgkmcnt(6)
	v_mov_b32_e32 v146, v77
	v_mov_b32_e32 v147, v76
	v_pk_add_f32 v[70:71], v[70:71], v[146:147]
	s_waitcnt lgkmcnt(5)
	v_mov_b32_e32 v76, v125
	v_mov_b32_e32 v77, v124
	v_pk_add_f32 v[70:71], v[70:71], v[76:77]
	s_waitcnt lgkmcnt(4)
	v_mov_b32_e32 v76, v131
	v_mov_b32_e32 v77, v130
	v_pk_add_f32 v[70:71], v[70:71], v[76:77]
	s_waitcnt lgkmcnt(3)
	v_mov_b32_e32 v76, v135
	v_mov_b32_e32 v77, v134
	v_pk_add_f32 v[70:71], v[70:71], v[76:77]
	s_waitcnt lgkmcnt(2)
	v_mov_b32_e32 v76, v141
	v_mov_b32_e32 v77, v140
	v_pk_add_f32 v[70:71], v[70:71], v[76:77]
	s_waitcnt lgkmcnt(1)
	v_mov_b32_e32 v76, v143
	v_mov_b32_e32 v77, v142
	v_pk_add_f32 v[70:71], v[70:71], v[76:77]
	s_waitcnt lgkmcnt(0)
	v_mov_b32_e32 v76, v145
	v_mov_b32_e32 v77, v144
	v_pk_add_f32 v[70:71], v[70:71], v[76:77]
	s_waitcnt vmcnt(9)
	v_lshlrev_b32_e32 v140, 16, v118
	v_pk_fma_f32 v[70:71], v[70:71], s[30:31], v[72:73] op_sel_hi:[1,0,0]
	v_and_b32_e32 v141, 0xffff0000, v118
	v_mul_f32_e32 v72, 0x4b800000, v71
	v_cmp_gt_f32_e32 vcc, s71, v71
	v_cmp_gt_f32_e64 s[8:9], s71, v70
	v_pk_mul_f32 v[102:103], v[138:139], v[102:103] op_sel_hi:[0,1]
	v_cndmask_b32_e32 v71, v71, v72, vcc
	v_rsq_f32_e32 v124, v71
	v_mul_f32_e32 v71, 0x4b800000, v70
	v_cndmask_b32_e64 v70, v70, v71, s[8:9]
	v_rsq_f32_e32 v125, v70
	global_load_dwordx4 v[70:73], v[74:75], off offset:144
	s_nop 0
	global_load_dwordx4 v[74:77], v[74:75], off offset:128
	v_mul_f32_e32 v130, 0x45800000, v124
	v_cndmask_b32_e32 v130, v124, v130, vcc
	v_mul_f32_e32 v124, 0x45800000, v125
	v_cndmask_b32_e64 v124, v125, v124, s[8:9]
	v_mul_f32_e32 v125, 0xbfb8aa3b, v140
	v_exp_f32_e32 v125, v125
	v_permlane16_swap_b32_e32 v104, v100
	v_permlane16_swap_b32_e32 v105, v101
	v_add_f32_e32 v118, 1.0, v125
	v_mul_f32_e32 v125, 0xbfb8aa3b, v141
	v_exp_f32_e32 v125, v125
	v_rcp_f32_e32 v142, v118
	v_pk_mul_f32 v[104:105], v[138:139], v[104:105] op_sel_hi:[0,1]
	v_pk_mul_f32 v[98:99], v[138:139], v[98:99] op_sel_hi:[0,1]
	v_add_f32_e32 v118, 1.0, v125
	v_rcp_f32_e32 v143, v118
	v_lshlrev_b32_e32 v118, 16, v119
	v_mul_f32_e32 v125, 0xbfb8aa3b, v118
	v_and_b32_e32 v119, 0xffff0000, v119
	v_exp_f32_e32 v125, v125
	v_mul_f32_e32 v131, 0xbfb8aa3b, v119
	v_exp_f32_e32 v131, v131
	v_mul_f32_e32 v149, 0x45800000, v148
	v_add_f32_e32 v125, 1.0, v125
	v_pk_mul_f32 v[100:101], v[138:139], v[100:101] op_sel_hi:[0,1]
	v_cndmask_b32_e64 v134, v148, v149, s[6:7]
	s_add_u32 s6, s44, s26
	v_ashrrev_i32_e32 v137, 31, v136
	s_addc_u32 s7, s45, 0
	v_lshl_add_u64 v[128:129], v[128:129], 1, s[6:7]
	v_lshlrev_b64 v[136:137], 12, v[136:137]
	s_waitcnt vmcnt(3)
	v_pk_mul_f32 v[98:99], v[98:99], v[78:79]
	s_waitcnt vmcnt(2)
	v_pk_mul_f32 v[102:103], v[102:103], v[106:107]
	v_pk_mul_f32 v[104:105], v[104:105], v[108:109]
	v_pk_mul_f32 v[102:103], v[102:103], v[140:141]
	v_rcp_f32_e32 v140, v125
	v_pk_mul_f32 v[102:103], v[102:103], v[142:143]
	v_add_f32_e32 v125, 1.0, v131
	v_lshlrev_b32_e32 v142, 16, v120
	v_and_b32_e32 v143, 0xffff0000, v120
	v_rcp_f32_e32 v141, v125
	v_mul_f32_e32 v125, 0xbfb8aa3b, v142
	v_pk_mul_f32 v[104:105], v[104:105], v[118:119]
	v_mul_f32_e32 v119, 0xbfb8aa3b, v143
	v_exp_f32_e32 v125, v125
	v_exp_f32_e32 v119, v119
	v_lshlrev_b32_e32 v120, 16, v121
	v_and_b32_e32 v121, 0xffff0000, v121
	v_add_f32_e32 v118, 1.0, v125
	v_add_f32_e32 v119, 1.0, v119
	v_mul_f32_e32 v125, 0xbfb8aa3b, v120
	v_mul_f32_e32 v131, 0xbfb8aa3b, v121
	v_rcp_f32_e32 v118, v118
	v_rcp_f32_e32 v119, v119
	v_exp_f32_e32 v125, v125
	v_exp_f32_e32 v131, v131
	v_pk_mul_f32 v[98:99], v[98:99], v[142:143]
	v_pk_mul_f32 v[100:101], v[100:101], v[80:81]
	v_pk_mul_f32 v[118:119], v[98:99], v[118:119]
	v_add_f32_e32 v98, 1.0, v125
	v_add_f32_e32 v99, 1.0, v131
	v_rcp_f32_e32 v98, v98
	v_rcp_f32_e32 v99, v99
	v_pk_mul_f32 v[100:101], v[100:101], v[120:121]
	v_pk_mul_f32 v[104:105], v[104:105], v[140:141]
	v_lshl_add_u64 v[136:137], v[128:129], 0, v[136:137]
	v_pk_mul_f32 v[120:121], v[100:101], v[98:99]
	v_cvt_pk_bf16_f32 v98, v102, v103
	v_cvt_pk_bf16_f32 v99, v104, v105
	v_cvt_pk_bf16_f32 v100, v118, v119
	v_cvt_pk_bf16_f32 v101, v120, v121
	v_ashrrev_i32_e32 v133, 31, v132
	v_ashrrev_i32_e32 v127, 31, v126
	v_ashrrev_i32_e32 v123, 31, v122
	global_store_dwordx4 v[136:137], v[98:101], off
	s_nop 1
	v_lshlrev_b32_e32 v98, 16, v114
	v_mul_f32_e32 v99, 0xbfb8aa3b, v98
	v_exp_f32_e32 v100, v99
	v_and_b32_e32 v99, 0xffff0000, v114
	v_permlane16_swap_b32_e32 v94, v90
	v_permlane16_swap_b32_e32 v95, v91
	v_mul_f32_e32 v101, 0xbfb8aa3b, v99
	v_lshlrev_b32_e32 v102, 16, v115
	v_exp_f32_e32 v101, v101
	v_pk_mul_f32 v[94:95], v[138:139], v[94:95] op_sel_hi:[0,1]
	v_mul_f32_e32 v103, 0xbfb8aa3b, v102
	s_waitcnt vmcnt(1)
	v_pk_mul_f32 v[94:95], v[94:95], v[74:75]
	v_exp_f32_e32 v104, v103
	v_and_b32_e32 v103, 0xffff0000, v115
	v_pk_mul_f32 v[94:95], v[94:95], v[98:99]
	v_mul_f32_e32 v99, 0xbfb8aa3b, v103
	v_exp_f32_e32 v99, v99
	v_add_f32_e32 v100, 1.0, v100
	v_add_f32_e32 v101, 1.0, v101
	v_rcp_f32_e32 v100, v100
	v_rcp_f32_e32 v101, v101
	v_add_f32_e32 v98, 1.0, v104
	v_add_f32_e32 v99, 1.0, v99
	v_permlane16_swap_b32_e32 v96, v92
	v_permlane16_swap_b32_e32 v97, v93
	v_rcp_f32_e32 v98, v98
	v_rcp_f32_e32 v99, v99
	v_pk_mul_f32 v[94:95], v[94:95], v[100:101]
	v_pk_mul_f32 v[96:97], v[138:139], v[96:97] op_sel_hi:[0,1]
	v_lshlrev_b32_e32 v100, 16, v116
	v_pk_mul_f32 v[96:97], v[96:97], v[76:77]
	v_mul_f32_e32 v101, 0xbfb8aa3b, v100
	v_exp_f32_e32 v104, v101
	v_pk_mul_f32 v[96:97], v[96:97], v[102:103]
	v_and_b32_e32 v101, 0xffff0000, v116
	v_pk_mul_f32 v[96:97], v[96:97], v[98:99]
	v_mul_f32_e32 v99, 0xbfb8aa3b, v101
	v_exp_f32_e32 v99, v99
	v_pk_mul_f32 v[90:91], v[138:139], v[90:91] op_sel_hi:[0,1]
	v_pk_mul_f32 v[90:91], v[90:91], v[70:71]
	v_add_f32_e32 v98, 1.0, v104
	v_pk_mul_f32 v[90:91], v[90:91], v[100:101]
	v_lshlrev_b32_e32 v100, 16, v117
	v_and_b32_e32 v101, 0xffff0000, v117
	v_add_f32_e32 v99, 1.0, v99
	v_mul_f32_e32 v102, 0xbfb8aa3b, v100
	v_mul_f32_e32 v103, 0xbfb8aa3b, v101
	v_rcp_f32_e32 v98, v98
	v_rcp_f32_e32 v99, v99
	v_exp_f32_e32 v102, v102
	v_exp_f32_e32 v103, v103
	v_pk_mul_f32 v[92:93], v[138:139], v[92:93] op_sel_hi:[0,1]
	v_pk_mul_f32 v[98:99], v[90:91], v[98:99]
	v_add_f32_e32 v90, 1.0, v102
	v_add_f32_e32 v91, 1.0, v103
	v_rcp_f32_e32 v90, v90
	v_rcp_f32_e32 v91, v91
	v_pk_mul_f32 v[92:93], v[92:93], v[72:73]
	s_nop 0
	v_pk_mul_f32 v[92:93], v[92:93], v[100:101]
	s_nop 0
	v_pk_mul_f32 v[100:101], v[92:93], v[90:91]
	v_cvt_pk_bf16_f32 v90, v94, v95
	v_cvt_pk_bf16_f32 v91, v96, v97
	v_cvt_pk_bf16_f32 v92, v98, v99
	v_cvt_pk_bf16_f32 v93, v100, v101
	global_store_dwordx4 v[136:137], v[90:93], off offset:64
	s_nop 1
	v_lshlrev_b32_e32 v92, 16, v110
	v_mul_f32_e32 v93, 0xbfb8aa3b, v92
	v_exp_f32_e32 v94, v93
	v_and_b32_e32 v93, 0xffff0000, v110
	v_permlane16_swap_b32_e32 v86, v66
	v_permlane16_swap_b32_e32 v87, v67
	v_mul_f32_e32 v95, 0xbfb8aa3b, v93
	v_lshlrev_b32_e32 v96, 16, v111
	v_exp_f32_e32 v95, v95
	v_pk_mul_f32 v[86:87], v[134:135], v[86:87] op_sel_hi:[0,1]
	v_mul_f32_e32 v97, 0xbfb8aa3b, v96
	v_pk_mul_f32 v[86:87], v[86:87], v[106:107]
	v_exp_f32_e32 v98, v97
	v_and_b32_e32 v97, 0xffff0000, v111
	v_pk_mul_f32 v[86:87], v[86:87], v[92:93]
	v_mul_f32_e32 v93, 0xbfb8aa3b, v97
	v_exp_f32_e32 v93, v93
	v_add_f32_e32 v94, 1.0, v94
	v_add_f32_e32 v95, 1.0, v95
	v_rcp_f32_e32 v94, v94
	v_rcp_f32_e32 v95, v95
	v_add_f32_e32 v92, 1.0, v98
	v_add_f32_e32 v93, 1.0, v93
	v_permlane16_swap_b32_e32 v88, v68
	v_permlane16_swap_b32_e32 v89, v69
	v_rcp_f32_e32 v92, v92
	v_rcp_f32_e32 v93, v93
	v_pk_mul_f32 v[86:87], v[86:87], v[94:95]
	v_pk_mul_f32 v[88:89], v[134:135], v[88:89] op_sel_hi:[0,1]
	v_lshlrev_b32_e32 v94, 16, v112
	v_pk_mul_f32 v[88:89], v[88:89], v[108:109]
	v_mul_f32_e32 v95, 0xbfb8aa3b, v94
	v_exp_f32_e32 v98, v95
	v_pk_mul_f32 v[88:89], v[88:89], v[96:97]
	v_and_b32_e32 v95, 0xffff0000, v112
	v_pk_mul_f32 v[88:89], v[88:89], v[92:93]
	v_mul_f32_e32 v93, 0xbfb8aa3b, v95
	v_exp_f32_e32 v93, v93
	v_pk_mul_f32 v[66:67], v[134:135], v[66:67] op_sel_hi:[0,1]
	v_pk_mul_f32 v[66:67], v[66:67], v[78:79]
	v_add_f32_e32 v92, 1.0, v98
	v_pk_mul_f32 v[66:67], v[66:67], v[94:95]
	v_lshlrev_b32_e32 v94, 16, v113
	v_and_b32_e32 v95, 0xffff0000, v113
	v_add_f32_e32 v93, 1.0, v93
	v_mul_f32_e32 v96, 0xbfb8aa3b, v94
	v_mul_f32_e32 v97, 0xbfb8aa3b, v95
	v_rcp_f32_e32 v92, v92
	v_rcp_f32_e32 v93, v93
	v_exp_f32_e32 v96, v96
	v_exp_f32_e32 v97, v97
	v_pk_mul_f32 v[68:69], v[134:135], v[68:69] op_sel_hi:[0,1]
	v_pk_mul_f32 v[92:93], v[66:67], v[92:93]
	v_add_f32_e32 v66, 1.0, v96
	v_add_f32_e32 v67, 1.0, v97
	v_rcp_f32_e32 v66, v66
	v_rcp_f32_e32 v67, v67
	v_pk_mul_f32 v[68:69], v[68:69], v[80:81]
	v_lshlrev_b64 v[90:91], 12, v[132:133]
	v_pk_mul_f32 v[68:69], v[68:69], v[94:95]
	v_lshl_add_u64 v[90:91], v[128:129], 0, v[90:91]
	v_pk_mul_f32 v[94:95], v[68:69], v[66:67]
	v_cvt_pk_bf16_f32 v66, v86, v87
	v_cvt_pk_bf16_f32 v67, v88, v89
	v_cvt_pk_bf16_f32 v68, v92, v93
	v_cvt_pk_bf16_f32 v69, v94, v95
	global_store_dwordx4 v[90:91], v[66:69], off
	s_nop 1
	v_lshlrev_b32_e32 v66, 16, v82
	v_mul_f32_e32 v67, 0xbfb8aa3b, v66
	v_exp_f32_e32 v68, v67
	v_and_b32_e32 v67, 0xffff0000, v82
	v_permlane16_swap_b32_e32 v46, v42
	v_permlane16_swap_b32_e32 v47, v43
	v_mul_f32_e32 v69, 0xbfb8aa3b, v67
	v_exp_f32_e32 v69, v69
	v_pk_mul_f32 v[46:47], v[134:135], v[46:47] op_sel_hi:[0,1]
	v_pk_mul_f32 v[46:47], v[46:47], v[74:75]
	v_lshlrev_b32_e32 v82, 16, v83
	v_and_b32_e32 v83, 0xffff0000, v83
	v_mul_f32_e32 v86, 0xbfb8aa3b, v82
	v_pk_mul_f32 v[46:47], v[46:47], v[66:67]
	v_mul_f32_e32 v67, 0xbfb8aa3b, v83
	v_exp_f32_e32 v86, v86
	v_exp_f32_e32 v67, v67
	v_add_f32_e32 v68, 1.0, v68
	v_add_f32_e32 v69, 1.0, v69
	v_rcp_f32_e32 v68, v68
	v_rcp_f32_e32 v69, v69
	v_add_f32_e32 v66, 1.0, v86
	v_add_f32_e32 v67, 1.0, v67
	v_permlane16_swap_b32_e32 v48, v44
	v_permlane16_swap_b32_e32 v49, v45
	v_rcp_f32_e32 v66, v66
	v_rcp_f32_e32 v67, v67
	v_pk_mul_f32 v[46:47], v[46:47], v[68:69]
	v_pk_mul_f32 v[48:49], v[134:135], v[48:49] op_sel_hi:[0,1]
	v_lshlrev_b32_e32 v68, 16, v84
	v_pk_mul_f32 v[48:49], v[48:49], v[76:77]
	v_mul_f32_e32 v69, 0xbfb8aa3b, v68
	v_exp_f32_e32 v86, v69
	v_pk_mul_f32 v[48:49], v[48:49], v[82:83]
	v_and_b32_e32 v69, 0xffff0000, v84
	v_pk_mul_f32 v[48:49], v[48:49], v[66:67]
	v_mul_f32_e32 v67, 0xbfb8aa3b, v69
	v_exp_f32_e32 v67, v67
	v_pk_mul_f32 v[42:43], v[134:135], v[42:43] op_sel_hi:[0,1]
	v_pk_mul_f32 v[42:43], v[42:43], v[70:71]
	v_add_f32_e32 v66, 1.0, v86
	v_pk_mul_f32 v[42:43], v[42:43], v[68:69]
	v_lshlrev_b32_e32 v68, 16, v85
	v_and_b32_e32 v69, 0xffff0000, v85
	v_add_f32_e32 v67, 1.0, v67
	v_mul_f32_e32 v82, 0xbfb8aa3b, v68
	v_mul_f32_e32 v83, 0xbfb8aa3b, v69
	v_rcp_f32_e32 v66, v66
	v_rcp_f32_e32 v67, v67
	v_exp_f32_e32 v82, v82
	v_exp_f32_e32 v83, v83
	v_pk_mul_f32 v[44:45], v[134:135], v[44:45] op_sel_hi:[0,1]
	v_pk_mul_f32 v[66:67], v[42:43], v[66:67]
	v_add_f32_e32 v42, 1.0, v82
	v_add_f32_e32 v43, 1.0, v83
	v_rcp_f32_e32 v42, v42
	v_rcp_f32_e32 v43, v43
	v_pk_mul_f32 v[44:45], v[44:45], v[72:73]
	s_nop 0
	v_pk_mul_f32 v[44:45], v[44:45], v[68:69]
	s_nop 0
	v_pk_mul_f32 v[68:69], v[44:45], v[42:43]
	v_cvt_pk_bf16_f32 v42, v46, v47
	v_cvt_pk_bf16_f32 v43, v48, v49
	v_cvt_pk_bf16_f32 v44, v66, v67
	v_cvt_pk_bf16_f32 v45, v68, v69
	global_store_dwordx4 v[90:91], v[42:45], off offset:64
	s_nop 1
	v_lshlrev_b32_e32 v44, 16, v62
	v_mul_f32_e32 v45, 0xbfb8aa3b, v44
	v_exp_f32_e32 v46, v45
	v_and_b32_e32 v45, 0xffff0000, v62
	v_permlane16_swap_b32_e32 v38, v34
	v_permlane16_swap_b32_e32 v39, v35
	v_mul_f32_e32 v47, 0xbfb8aa3b, v45
	v_lshlrev_b32_e32 v48, 16, v63
	v_exp_f32_e32 v47, v47
	v_pk_mul_f32 v[38:39], v[130:131], v[38:39] op_sel_hi:[0,1]
	v_mul_f32_e32 v49, 0xbfb8aa3b, v48
	v_pk_mul_f32 v[38:39], v[38:39], v[106:107]
	v_exp_f32_e32 v62, v49
	v_and_b32_e32 v49, 0xffff0000, v63
	v_pk_mul_f32 v[38:39], v[38:39], v[44:45]
	v_mul_f32_e32 v45, 0xbfb8aa3b, v49
	v_exp_f32_e32 v45, v45
	v_add_f32_e32 v46, 1.0, v46
	v_add_f32_e32 v47, 1.0, v47
	v_rcp_f32_e32 v46, v46
	v_rcp_f32_e32 v47, v47
	v_add_f32_e32 v44, 1.0, v62
	v_add_f32_e32 v45, 1.0, v45
	v_permlane16_swap_b32_e32 v40, v36
	v_permlane16_swap_b32_e32 v41, v37
	v_rcp_f32_e32 v44, v44
	v_rcp_f32_e32 v45, v45
	v_pk_mul_f32 v[38:39], v[38:39], v[46:47]
	v_pk_mul_f32 v[40:41], v[130:131], v[40:41] op_sel_hi:[0,1]
	v_lshlrev_b32_e32 v46, 16, v64
	v_pk_mul_f32 v[40:41], v[40:41], v[108:109]
	v_mul_f32_e32 v47, 0xbfb8aa3b, v46
	v_exp_f32_e32 v62, v47
	v_pk_mul_f32 v[40:41], v[40:41], v[48:49]
	v_and_b32_e32 v47, 0xffff0000, v64
	v_pk_mul_f32 v[40:41], v[40:41], v[44:45]
	v_mul_f32_e32 v45, 0xbfb8aa3b, v47
	v_exp_f32_e32 v45, v45
	v_pk_mul_f32 v[34:35], v[130:131], v[34:35] op_sel_hi:[0,1]
	v_pk_mul_f32 v[34:35], v[34:35], v[78:79]
	v_add_f32_e32 v44, 1.0, v62
	v_pk_mul_f32 v[34:35], v[34:35], v[46:47]
	v_lshlrev_b32_e32 v46, 16, v65
	v_and_b32_e32 v47, 0xffff0000, v65
	v_add_f32_e32 v45, 1.0, v45
	v_mul_f32_e32 v48, 0xbfb8aa3b, v46
	v_mul_f32_e32 v49, 0xbfb8aa3b, v47
	v_rcp_f32_e32 v44, v44
	v_rcp_f32_e32 v45, v45
	v_exp_f32_e32 v48, v48
	v_exp_f32_e32 v49, v49
	v_pk_mul_f32 v[36:37], v[130:131], v[36:37] op_sel_hi:[0,1]
	v_pk_mul_f32 v[44:45], v[34:35], v[44:45]
	v_add_f32_e32 v34, 1.0, v48
	v_add_f32_e32 v35, 1.0, v49
	v_rcp_f32_e32 v34, v34
	v_rcp_f32_e32 v35, v35
	v_pk_mul_f32 v[36:37], v[36:37], v[80:81]
	v_lshlrev_b64 v[42:43], 12, v[126:127]
	v_pk_mul_f32 v[36:37], v[36:37], v[46:47]
	v_lshl_add_u64 v[42:43], v[128:129], 0, v[42:43]
	v_pk_mul_f32 v[46:47], v[36:37], v[34:35]
	v_cvt_pk_bf16_f32 v34, v38, v39
	v_cvt_pk_bf16_f32 v35, v40, v41
	v_cvt_pk_bf16_f32 v36, v44, v45
	v_cvt_pk_bf16_f32 v37, v46, v47
	global_store_dwordx4 v[42:43], v[34:37], off
	s_nop 1
	v_lshlrev_b32_e32 v34, 16, v58
	v_mul_f32_e32 v35, 0xbfb8aa3b, v34
	v_exp_f32_e32 v36, v35
	v_and_b32_e32 v35, 0xffff0000, v58
	v_permlane16_swap_b32_e32 v30, v26
	v_permlane16_swap_b32_e32 v31, v27
	v_mul_f32_e32 v37, 0xbfb8aa3b, v35
	v_lshlrev_b32_e32 v38, 16, v59
	v_exp_f32_e32 v37, v37
	v_pk_mul_f32 v[30:31], v[130:131], v[30:31] op_sel_hi:[0,1]
	v_mul_f32_e32 v39, 0xbfb8aa3b, v38
	v_pk_mul_f32 v[30:31], v[30:31], v[74:75]
	v_exp_f32_e32 v40, v39
	v_and_b32_e32 v39, 0xffff0000, v59
	v_pk_mul_f32 v[30:31], v[30:31], v[34:35]
	v_mul_f32_e32 v35, 0xbfb8aa3b, v39
	v_exp_f32_e32 v35, v35
	v_add_f32_e32 v36, 1.0, v36
	v_add_f32_e32 v37, 1.0, v37
	v_rcp_f32_e32 v36, v36
	v_rcp_f32_e32 v37, v37
	v_add_f32_e32 v34, 1.0, v40
	v_add_f32_e32 v35, 1.0, v35
	v_permlane16_swap_b32_e32 v32, v28
	v_permlane16_swap_b32_e32 v33, v29
	v_rcp_f32_e32 v34, v34
	v_rcp_f32_e32 v35, v35
	v_pk_mul_f32 v[30:31], v[30:31], v[36:37]
	v_pk_mul_f32 v[32:33], v[130:131], v[32:33] op_sel_hi:[0,1]
	v_lshlrev_b32_e32 v36, 16, v60
	v_pk_mul_f32 v[32:33], v[32:33], v[76:77]
	v_mul_f32_e32 v37, 0xbfb8aa3b, v36
	v_exp_f32_e32 v40, v37
	v_pk_mul_f32 v[32:33], v[32:33], v[38:39]
	v_and_b32_e32 v37, 0xffff0000, v60
	v_pk_mul_f32 v[32:33], v[32:33], v[34:35]
	v_mul_f32_e32 v35, 0xbfb8aa3b, v37
	v_exp_f32_e32 v35, v35
	v_pk_mul_f32 v[26:27], v[130:131], v[26:27] op_sel_hi:[0,1]
	v_pk_mul_f32 v[26:27], v[26:27], v[70:71]
	v_add_f32_e32 v34, 1.0, v40
	v_pk_mul_f32 v[26:27], v[26:27], v[36:37]
	v_lshlrev_b32_e32 v36, 16, v61
	v_and_b32_e32 v37, 0xffff0000, v61
	v_add_f32_e32 v35, 1.0, v35
	v_mul_f32_e32 v38, 0xbfb8aa3b, v36
	v_mul_f32_e32 v39, 0xbfb8aa3b, v37
	v_rcp_f32_e32 v34, v34
	v_rcp_f32_e32 v35, v35
	v_exp_f32_e32 v38, v38
	v_exp_f32_e32 v39, v39
	v_pk_mul_f32 v[28:29], v[130:131], v[28:29] op_sel_hi:[0,1]
	v_pk_mul_f32 v[34:35], v[26:27], v[34:35]
	v_add_f32_e32 v26, 1.0, v38
	v_add_f32_e32 v27, 1.0, v39
	v_rcp_f32_e32 v26, v26
	v_rcp_f32_e32 v27, v27
	v_pk_mul_f32 v[28:29], v[28:29], v[72:73]
	s_nop 0
	v_pk_mul_f32 v[28:29], v[28:29], v[36:37]
	s_nop 0
	v_pk_mul_f32 v[36:37], v[28:29], v[26:27]
	v_cvt_pk_bf16_f32 v26, v30, v31
	v_cvt_pk_bf16_f32 v27, v32, v33
	v_cvt_pk_bf16_f32 v28, v34, v35
	v_cvt_pk_bf16_f32 v29, v36, v37
	global_store_dwordx4 v[42:43], v[26:29], off offset:64
	s_nop 1
	v_lshlrev_b32_e32 v28, 16, v54
	v_mul_f32_e32 v29, 0xbfb8aa3b, v28
	v_exp_f32_e32 v30, v29
	v_and_b32_e32 v29, 0xffff0000, v54
	v_permlane16_swap_b32_e32 v14, v10
	v_permlane16_swap_b32_e32 v15, v11
	v_mul_f32_e32 v31, 0xbfb8aa3b, v29
	v_lshlrev_b32_e32 v32, 16, v55
	v_exp_f32_e32 v31, v31
	v_pk_mul_f32 v[14:15], v[124:125], v[14:15] op_sel_hi:[0,1]
	v_mul_f32_e32 v33, 0xbfb8aa3b, v32
	v_pk_mul_f32 v[14:15], v[14:15], v[106:107]
	v_exp_f32_e32 v34, v33
	v_and_b32_e32 v33, 0xffff0000, v55
	v_pk_mul_f32 v[14:15], v[14:15], v[28:29]
	v_mul_f32_e32 v29, 0xbfb8aa3b, v33
	v_exp_f32_e32 v29, v29
	v_add_f32_e32 v30, 1.0, v30
	v_add_f32_e32 v31, 1.0, v31
	v_rcp_f32_e32 v30, v30
	v_rcp_f32_e32 v31, v31
	v_add_f32_e32 v28, 1.0, v34
	v_add_f32_e32 v29, 1.0, v29
	v_permlane16_swap_b32_e32 v16, v12
	v_permlane16_swap_b32_e32 v17, v13
	v_rcp_f32_e32 v28, v28
	v_rcp_f32_e32 v29, v29
	v_pk_mul_f32 v[14:15], v[14:15], v[30:31]
	v_pk_mul_f32 v[16:17], v[124:125], v[16:17] op_sel_hi:[0,1]
	v_lshlrev_b32_e32 v30, 16, v56
	v_pk_mul_f32 v[16:17], v[16:17], v[108:109]
	v_mul_f32_e32 v31, 0xbfb8aa3b, v30
	v_exp_f32_e32 v34, v31
	v_pk_mul_f32 v[16:17], v[16:17], v[32:33]
	v_and_b32_e32 v31, 0xffff0000, v56
	v_pk_mul_f32 v[16:17], v[16:17], v[28:29]
	v_mul_f32_e32 v29, 0xbfb8aa3b, v31
	v_exp_f32_e32 v29, v29
	v_pk_mul_f32 v[10:11], v[124:125], v[10:11] op_sel_hi:[0,1]
	v_pk_mul_f32 v[10:11], v[10:11], v[78:79]
	v_add_f32_e32 v28, 1.0, v34
	v_pk_mul_f32 v[10:11], v[10:11], v[30:31]
	v_lshlrev_b32_e32 v30, 16, v57
	v_and_b32_e32 v31, 0xffff0000, v57
	v_add_f32_e32 v29, 1.0, v29
	v_mul_f32_e32 v32, 0xbfb8aa3b, v30
	v_mul_f32_e32 v33, 0xbfb8aa3b, v31
	v_rcp_f32_e32 v28, v28
	v_rcp_f32_e32 v29, v29
	v_exp_f32_e32 v32, v32
	v_exp_f32_e32 v33, v33
	v_pk_mul_f32 v[12:13], v[124:125], v[12:13] op_sel_hi:[0,1]
	v_pk_mul_f32 v[28:29], v[10:11], v[28:29]
	v_add_f32_e32 v10, 1.0, v32
	v_add_f32_e32 v11, 1.0, v33
	v_rcp_f32_e32 v10, v10
	v_rcp_f32_e32 v11, v11
	v_pk_mul_f32 v[12:13], v[12:13], v[80:81]
	v_lshlrev_b64 v[26:27], 12, v[122:123]
	v_pk_mul_f32 v[12:13], v[12:13], v[30:31]
	v_lshl_add_u64 v[26:27], v[128:129], 0, v[26:27]
	v_pk_mul_f32 v[30:31], v[12:13], v[10:11]
	v_cvt_pk_bf16_f32 v10, v14, v15
	v_cvt_pk_bf16_f32 v11, v16, v17
	v_cvt_pk_bf16_f32 v12, v28, v29
	v_cvt_pk_bf16_f32 v13, v30, v31
	global_store_dwordx4 v[26:27], v[10:13], off
	s_nop 1
	v_lshlrev_b32_e32 v10, 16, v50
	v_mul_f32_e32 v11, 0xbfb8aa3b, v10
	v_exp_f32_e32 v12, v11
	v_and_b32_e32 v11, 0xffff0000, v50
	v_permlane16_swap_b32_e32 v6, v2
	v_permlane16_swap_b32_e32 v7, v3
	v_mul_f32_e32 v13, 0xbfb8aa3b, v11
	v_lshlrev_b32_e32 v14, 16, v51
	v_exp_f32_e32 v13, v13
	v_pk_mul_f32 v[6:7], v[124:125], v[6:7] op_sel_hi:[0,1]
	v_mul_f32_e32 v15, 0xbfb8aa3b, v14
	v_pk_mul_f32 v[6:7], v[6:7], v[74:75]
	v_exp_f32_e32 v16, v15
	v_and_b32_e32 v15, 0xffff0000, v51
	v_pk_mul_f32 v[6:7], v[6:7], v[10:11]
	v_mul_f32_e32 v11, 0xbfb8aa3b, v15
	v_exp_f32_e32 v11, v11
	v_add_f32_e32 v12, 1.0, v12
	v_add_f32_e32 v13, 1.0, v13
	v_rcp_f32_e32 v12, v12
	v_rcp_f32_e32 v13, v13
	v_add_f32_e32 v10, 1.0, v16
	v_add_f32_e32 v11, 1.0, v11
	v_permlane16_swap_b32_e32 v8, v4
	v_permlane16_swap_b32_e32 v9, v5
	v_rcp_f32_e32 v10, v10
	v_rcp_f32_e32 v11, v11
	v_pk_mul_f32 v[6:7], v[6:7], v[12:13]
	v_pk_mul_f32 v[8:9], v[124:125], v[8:9] op_sel_hi:[0,1]
	v_lshlrev_b32_e32 v12, 16, v52
	v_pk_mul_f32 v[8:9], v[8:9], v[76:77]
	v_mul_f32_e32 v13, 0xbfb8aa3b, v12
	v_exp_f32_e32 v16, v13
	v_pk_mul_f32 v[8:9], v[8:9], v[14:15]
	v_and_b32_e32 v13, 0xffff0000, v52
	v_pk_mul_f32 v[8:9], v[8:9], v[10:11]
	v_mul_f32_e32 v11, 0xbfb8aa3b, v13
	v_exp_f32_e32 v11, v11
	v_pk_mul_f32 v[2:3], v[124:125], v[2:3] op_sel_hi:[0,1]
	v_pk_mul_f32 v[2:3], v[2:3], v[70:71]
	v_add_f32_e32 v10, 1.0, v16
	v_pk_mul_f32 v[2:3], v[2:3], v[12:13]
	v_lshlrev_b32_e32 v12, 16, v53
	v_and_b32_e32 v13, 0xffff0000, v53
	v_add_f32_e32 v11, 1.0, v11
	v_mul_f32_e32 v14, 0xbfb8aa3b, v12
	v_mul_f32_e32 v15, 0xbfb8aa3b, v13
	v_rcp_f32_e32 v10, v10
	v_rcp_f32_e32 v11, v11
	v_exp_f32_e32 v14, v14
	v_exp_f32_e32 v15, v15
	v_pk_mul_f32 v[4:5], v[124:125], v[4:5] op_sel_hi:[0,1]
	v_pk_mul_f32 v[10:11], v[2:3], v[10:11]
	v_add_f32_e32 v2, 1.0, v14
	v_add_f32_e32 v3, 1.0, v15
	v_rcp_f32_e32 v2, v2
	v_rcp_f32_e32 v3, v3
	v_pk_mul_f32 v[4:5], v[4:5], v[72:73]
	s_nop 0
	v_pk_mul_f32 v[4:5], v[4:5], v[12:13]
	s_nop 0
	v_pk_mul_f32 v[12:13], v[4:5], v[2:3]
	v_cvt_pk_bf16_f32 v2, v6, v7
	v_cvt_pk_bf16_f32 v3, v8, v9
	v_cvt_pk_bf16_f32 v4, v10, v11
	v_cvt_pk_bf16_f32 v5, v12, v13
	global_store_dwordx4 v[26:27], v[2:5], off offset:64
	s_add_i32 s60, s60, 16
	s_add_i32 s61, s61, 64
	s_add_i32 s62, s62, 32
	s_and_b64 vcc, exec, s[10:11]
	s_cbranch_vccnz .LBB0_496

.LBB0_496:
	s_setprio 0
	s_lshl_b32 s4, s2, 3
	s_add_i32 s30, s54, s4
	s_mul_i32 s4, s54, 0x2100
	v_and_b32_e32 v3, 63, v168
	s_add_i32 s31, s4, 0
	s_cmpk_gt_i32 s30, 0xbff
	v_lshrrev_b32_e32 v2, 5, v3
	v_and_b32_e32 v4, 31, v168
	v_lshrrev_b32_e32 v46, 3, v3
	v_lshlrev_b32_e32 v5, 3, v3
	s_barrier
	s_cbranch_scc1 .LBB0_673
	s_movk_i32 s4, 0x84
	v_mov_b32_e32 v3, 0x210
	v_mad_u32_u24 v49, v2, s4, v3
	v_mov_b32_e32 v3, 0x420
	v_mad_u32_u24 v50, v2, s4, v3
	v_mov_b32_e32 v3, 0x630
	v_mad_u32_u24 v51, v2, s4, v3
	v_mov_b32_e32 v3, 0x840
	v_mad_u32_u24 v52, v2, s4, v3
	v_mov_b32_e32 v3, 0xa50
	v_mad_u32_u24 v53, v2, s4, v3
	v_mov_b32_e32 v3, 0xc60
	v_mad_u32_u24 v54, v2, s4, v3
	v_mov_b32_e32 v3, 0xe70
	s_load_dwordx8 s[8:15], s[18:19], 0x38
	v_mad_u32_u24 v55, v2, s4, v3
	v_mov_b32_e32 v3, 0x1080
	v_mad_u32_u24 v56, v2, s4, v3
	v_mov_b32_e32 v3, 0x1290
	v_mad_u32_u24 v57, v2, s4, v3
	v_mov_b32_e32 v3, 0x14a0
	v_mad_u32_u24 v58, v2, s4, v3
	v_mov_b32_e32 v3, 0x16b0
	v_mad_u32_u24 v59, v2, s4, v3
	v_mov_b32_e32 v3, 0x18c0
	s_waitcnt lgkmcnt(0)
	s_cmp_lg_u64 s[8:9], 0
	v_mad_u32_u24 v60, v2, s4, v3
	v_and_b32_e32 v3, 56, v5
	v_mov_b32_e32 v7, 0
	s_cselect_b64 s[6:7], -1, 0
	v_mul_u32_u24_e32 v10, 0x84, v3
	v_lshlrev_b32_e32 v6, 1, v3
	v_lshlrev_b32_e32 v3, 2, v46
	s_cmp_lg_u64 s[12:13], 0
	v_lshl_add_u32 v47, v4, 2, s31
	v_mul_u32_u24_e32 v48, 0x84, v2
	v_lshl_add_u64 v[8:9], s[16:17], 0, v[6:7]
	v_add3_u32 v61, s31, v10, v3
	v_or_b32_e32 v62, 8, v46
	v_or_b32_e32 v63, 16, v46
	v_or_b32_e32 v64, 24, v46
	s_cselect_b64 s[20:21], -1, 0
	v_mov_b32_e32 v3, v7
	s_mov_b32 s33, 0xc000
	s_mov_b32 s34, 0x30000
	s_mov_b32 s35, 0x60000
	s_mov_b32 s36, 0x90000
	s_mov_b32 s37, 0xc0000
	s_mov_b32 s38, 0xf0000
	s_mov_b32 s39, 0x120000
	s_mov_b32 s44, 0x150000
	s_mov_b32 s45, 0x180000
	s_mov_b32 s46, 0x1b0000
	v_cndmask_b32_e64 v65, 0, 1, s[6:7]
	s_mov_b32 s47, 0x10000
	s_mov_b32 s48, 0x20000
	s_mov_b32 s49, 0x40000
	s_mov_b32 s50, 0x50000
	s_mov_b32 s51, 0x70000
	s_mov_b32 s57, 0x80000
	s_mov_b32 s59, 0xa0000
	s_mov_b32 s60, 0xb0000
	s_mov_b32 s61, 0xd0000
	s_mov_b32 s62, 0xe0000
	s_mov_b32 s63, 0x100000
	s_mov_b32 s64, 0x110000
	s_mov_b32 s65, 0x130000
	s_mov_b32 s66, 0x140000
	s_mov_b32 s67, 0x160000
	s_mov_b32 s68, 0x170000
	s_mov_b32 s69, 0x190000
	s_mov_b32 s70, 0x1a0000
	v_lshlrev_b32_e32 v6, 2, v4
	v_mov_b32_e32 v11, 0x3e0293ee
	s_mov_b32 s71, s30
	s_branch .LBB0_501
